# GEMM1 rotary-q epilogue: all 16 cos/sin table loads issued ahead of the first row group (counted vmcnt(14)) instead of load, vmcnt(0), use per group
# speedup vs baseline: 1.0011x; 1.0011x over previous
.LBB0_586:
	s_andn2_b64 vcc, exec, s[4:5]
	s_cbranch_vccnz .LBB0_588
	s_lshl_b32 s4, s90, 8
	s_add_i32 s4, s4, s57
	v_lshl_add_u32 v130, v185, 3, s59
	v_add_u32_e32 v128, s4, v184
	v_ashrrev_i32_e32 v132, 1, v130
	v_ashrrev_i32_e32 v129, 31, v128
	v_ashrrev_i32_e32 v133, 31, v132
	v_lshlrev_b64 v[134:135], 8, v[128:129]
	v_lshl_add_u64 v[138:139], s[12:13], 0, v[134:135]
	v_lshlrev_b64 v[136:137], 2, v[132:133]
	v_lshl_add_u64 v[132:133], v[138:139], 0, v[136:137]
	global_load_dwordx4 v[138:141], v[132:133], off
	v_lshl_add_u64 v[132:133], s[14:15], 0, v[134:135]
	v_lshl_add_u64 v[132:133], v[132:133], 0, v[136:137]
	global_load_dwordx4 v[142:145], v[132:133], off
	v_add_u32_e32 v250, v134, v136
	v_add_u32_e32 v251, 0x1000, v250
	global_load_dwordx4 v[190:193], v251, s[12:13]
	global_load_dwordx4 v[194:197], v251, s[14:15]
	v_add_u32_e32 v251, 0x2000, v250
	global_load_dwordx4 v[198:201], v251, s[12:13]
	global_load_dwordx4 v[202:205], v251, s[14:15]
	v_add_u32_e32 v251, 0x3000, v250
	global_load_dwordx4 v[210:213], v251, s[12:13]
	global_load_dwordx4 v[214:217], v251, s[14:15]
	v_add_u32_e32 v251, 0x8000, v250
	global_load_dwordx4 v[218:221], v251, s[12:13]
	global_load_dwordx4 v[222:225], v251, s[14:15]
	v_add_u32_e32 v251, 0x9000, v250
	global_load_dwordx4 v[226:229], v251, s[12:13]
	global_load_dwordx4 v[230:233], v251, s[14:15]
	v_add_u32_e32 v251, 0xa000, v250
	global_load_dwordx4 v[234:237], v251, s[12:13]
	global_load_dwordx4 v[238:241], v251, s[14:15]
	v_add_u32_e32 v251, 0xb000, v250
	global_load_dwordx4 v[242:245], v251, s[12:13]
	global_load_dwordx4 v[246:249], v251, s[14:15]
	v_ashrrev_i32_e32 v131, 31, v130
	s_waitcnt vmcnt(14)
	v_mov_b32_e32 v146, v141
	v_mov_b32_e32 v156, v145
	v_pk_mul_f32 v[132:133], v[120:121], v[144:145] op_sel_hi:[1,0]
	v_pk_mul_f32 v[168:169], v[122:123], v[156:157] op_sel_hi:[1,0]
	v_pk_fma_f32 v[134:135], v[120:121], v[140:141], v[132:133] op_sel:[0,0,1] op_sel_hi:[1,1,0] neg_lo:[0,0,1] neg_hi:[0,0,1]
	v_pk_fma_f32 v[132:133], v[120:121], v[140:141], v[132:133] op_sel:[0,0,1] op_sel_hi:[1,0,0]
	v_pk_fma_f32 v[170:171], v[122:123], v[146:147], v[168:169] op_sel:[0,0,1] op_sel_hi:[1,0,0]
	v_pk_fma_f32 v[172:173], v[122:123], v[146:147], v[168:169] op_sel:[0,0,1] op_sel_hi:[1,0,0] neg_lo:[0,0,1] neg_hi:[0,0,1]
	v_cvt_pk_bf16_f32 v170, v134, v133
	v_mov_b64_e32 v[132:133], s[0:1]
	v_mad_i64_i32 v[134:135], s[4:5], v128, s28, v[132:133]
	s_lshl_b32 s4, s82, 8
	s_ashr_i32 s5, s4, 31
	v_pk_mul_f32 v[168:169], v[124:125], v[142:143] op_sel_hi:[1,0]
	v_pk_mul_f32 v[176:177], v[126:127], v[142:143] op_sel:[0,1]
	s_lshl_b64 s[4:5], s[4:5], 1
	v_pk_fma_f32 v[174:175], v[124:125], v[138:139], v[168:169] op_sel:[0,0,1] op_sel_hi:[1,1,0] neg_lo:[0,0,1] neg_hi:[0,0,1]
	v_pk_fma_f32 v[168:169], v[124:125], v[138:139], v[168:169] op_sel:[0,0,1] op_sel_hi:[1,0,0]
	v_pk_fma_f32 v[186:187], v[126:127], v[138:139], v[176:177] op_sel:[0,1,1] op_sel_hi:[1,1,0] neg_lo:[0,0,1] neg_hi:[0,0,1]
	v_pk_fma_f32 v[176:177], v[126:127], v[138:139], v[176:177] op_sel:[0,1,1] op_sel_hi:[1,1,0]
	v_cvt_pk_bf16_f32 v171, v172, v171
	v_lshl_add_u64 v[172:173], v[134:135], 0, s[4:5]
	v_lshlrev_b64 v[134:135], 1, v[130:131]
	v_cvt_pk_bf16_f32 v168, v174, v169
	v_cvt_pk_bf16_f32 v169, v186, v177
	v_lshl_add_u64 v[130:131], v[172:173], 0, v[134:135]
	v_pk_mul_f32 v[144:145], v[112:113], v[144:145] op_sel_hi:[1,0]
	global_store_dwordx4 v[130:131], v[168:171], off
	s_nop 1
	v_pk_fma_f32 v[168:169], v[112:113], v[140:141], v[144:145] op_sel:[0,0,1] op_sel_hi:[1,1,0] neg_lo:[0,0,1] neg_hi:[0,0,1]
	v_pk_fma_f32 v[140:141], v[112:113], v[140:141], v[144:145] op_sel:[0,0,1] op_sel_hi:[1,0,0]
	v_pk_mul_f32 v[144:145], v[114:115], v[156:157] op_sel_hi:[1,0]
	v_cvt_pk_bf16_f32 v140, v168, v141
	v_pk_fma_f32 v[170:171], v[114:115], v[146:147], v[144:145] op_sel:[0,0,1] op_sel_hi:[1,0,0] neg_lo:[0,0,1] neg_hi:[0,0,1]
	v_pk_fma_f32 v[144:145], v[114:115], v[146:147], v[144:145] op_sel:[0,0,1] op_sel_hi:[1,0,0]
	v_pk_mul_f32 v[146:147], v[116:117], v[142:143] op_sel_hi:[1,0]
	v_pk_mul_f32 v[142:143], v[118:119], v[142:143] op_sel:[0,1]
	v_pk_fma_f32 v[172:173], v[116:117], v[138:139], v[146:147] op_sel:[0,0,1] op_sel_hi:[1,1,0] neg_lo:[0,0,1] neg_hi:[0,0,1]
	v_pk_fma_f32 v[146:147], v[116:117], v[138:139], v[146:147] op_sel:[0,0,1] op_sel_hi:[1,0,0]
	v_pk_fma_f32 v[174:175], v[118:119], v[138:139], v[142:143] op_sel:[0,1,1] op_sel_hi:[1,1,0] neg_lo:[0,0,1] neg_hi:[0,0,1]
	v_pk_fma_f32 v[138:139], v[118:119], v[138:139], v[142:143] op_sel:[0,1,1] op_sel_hi:[1,1,0]
	v_cvt_pk_bf16_f32 v141, v170, v145
	v_cvt_pk_bf16_f32 v138, v172, v147
	v_cvt_pk_bf16_f32 v139, v174, v139
	global_store_dwordx4 v[130:131], v[138:141], off offset:256
	v_add_u32_e32 v130, 16, v128
	v_ashrrev_i32_e32 v131, 31, v130
	v_lshlrev_b64 v[142:143], 8, v[130:131]
	v_lshl_add_u64 v[138:139], s[12:13], 0, v[142:143]
	v_lshl_add_u64 v[142:143], s[14:15], 0, v[142:143]
	v_lshl_add_u64 v[138:139], v[138:139], 0, v[136:137]
	v_lshl_add_u64 v[142:143], v[142:143], 0, v[136:137]
	v_mad_i64_i32 v[130:131], s[6:7], v130, s28, v[132:133]
	v_lshl_add_u64 v[130:131], v[130:131], 0, s[4:5]
	v_lshl_add_u64 v[130:131], v[130:131], 0, v[134:135]
	s_waitcnt vmcnt(14)
	v_mov_b32_e32 v138, v190
	v_mov_b32_e32 v139, v191
	v_mov_b32_e32 v140, v192
	v_mov_b32_e32 v141, v193
	v_mov_b32_e32 v142, v194
	v_mov_b32_e32 v143, v195
	v_mov_b32_e32 v144, v196
	v_mov_b32_e32 v145, v197
	v_pk_mul_f32 v[146:147], v[104:105], v[144:145] op_sel_hi:[1,0]
	s_nop 0
	v_pk_fma_f32 v[170:171], v[104:105], v[140:141], v[146:147] op_sel:[0,0,1] op_sel_hi:[1,1,0] neg_lo:[0,0,1] neg_hi:[0,0,1]
	v_pk_fma_f32 v[146:147], v[104:105], v[140:141], v[146:147] op_sel:[0,0,1] op_sel_hi:[1,0,0]
	v_mov_b32_e32 v156, v145
	v_mov_b32_e32 v146, v141
	v_pk_mul_f32 v[168:169], v[106:107], v[156:157] op_sel_hi:[1,0]
	v_pk_mul_f32 v[186:187], v[110:111], v[142:143] op_sel:[0,1]
	v_pk_fma_f32 v[172:173], v[106:107], v[146:147], v[168:169] op_sel:[0,0,1] op_sel_hi:[1,0,0] neg_lo:[0,0,1] neg_hi:[0,0,1]
	v_pk_fma_f32 v[174:175], v[106:107], v[146:147], v[168:169] op_sel:[0,0,1] op_sel_hi:[1,0,0]
	v_pk_mul_f32 v[168:169], v[108:109], v[142:143] op_sel_hi:[1,0]
	v_pk_fma_f32 v[188:189], v[110:111], v[138:139], v[186:187] op_sel:[0,1,1] op_sel_hi:[1,1,0] neg_lo:[0,0,1] neg_hi:[0,0,1]
	v_pk_fma_f32 v[176:177], v[108:109], v[138:139], v[168:169] op_sel:[0,0,1] op_sel_hi:[1,1,0] neg_lo:[0,0,1] neg_hi:[0,0,1]
	v_pk_fma_f32 v[168:169], v[108:109], v[138:139], v[168:169] op_sel:[0,0,1] op_sel_hi:[1,0,0]
	v_pk_fma_f32 v[186:187], v[110:111], v[138:139], v[186:187] op_sel:[0,1,1] op_sel_hi:[1,1,0]
	v_cvt_pk_bf16_f32 v168, v176, v169
	v_cvt_pk_bf16_f32 v169, v188, v187
	v_cvt_pk_bf16_f32 v170, v170, v147
	v_cvt_pk_bf16_f32 v171, v172, v175
	v_pk_mul_f32 v[144:145], v[96:97], v[144:145] op_sel_hi:[1,0]
	global_store_dwordx4 v[130:131], v[168:171], off
	s_nop 1
	v_pk_fma_f32 v[168:169], v[96:97], v[140:141], v[144:145] op_sel:[0,0,1] op_sel_hi:[1,1,0] neg_lo:[0,0,1] neg_hi:[0,0,1]
	v_pk_fma_f32 v[140:141], v[96:97], v[140:141], v[144:145] op_sel:[0,0,1] op_sel_hi:[1,0,0]
	v_pk_mul_f32 v[144:145], v[98:99], v[156:157] op_sel_hi:[1,0]
	v_cvt_pk_bf16_f32 v140, v168, v141
	v_pk_fma_f32 v[170:171], v[98:99], v[146:147], v[144:145] op_sel:[0,0,1] op_sel_hi:[1,0,0] neg_lo:[0,0,1] neg_hi:[0,0,1]
	v_pk_fma_f32 v[144:145], v[98:99], v[146:147], v[144:145] op_sel:[0,0,1] op_sel_hi:[1,0,0]
	v_pk_mul_f32 v[146:147], v[100:101], v[142:143] op_sel_hi:[1,0]
	v_pk_mul_f32 v[142:143], v[102:103], v[142:143] op_sel:[0,1]
	v_pk_fma_f32 v[172:173], v[100:101], v[138:139], v[146:147] op_sel:[0,0,1] op_sel_hi:[1,1,0] neg_lo:[0,0,1] neg_hi:[0,0,1]
	v_pk_fma_f32 v[146:147], v[100:101], v[138:139], v[146:147] op_sel:[0,0,1] op_sel_hi:[1,0,0]
	v_pk_fma_f32 v[174:175], v[102:103], v[138:139], v[142:143] op_sel:[0,1,1] op_sel_hi:[1,1,0] neg_lo:[0,0,1] neg_hi:[0,0,1]
	v_pk_fma_f32 v[138:139], v[102:103], v[138:139], v[142:143] op_sel:[0,1,1] op_sel_hi:[1,1,0]
	v_cvt_pk_bf16_f32 v141, v170, v145
	v_cvt_pk_bf16_f32 v138, v172, v147
	v_cvt_pk_bf16_f32 v139, v174, v139
	global_store_dwordx4 v[130:131], v[138:141], off offset:256
	v_add_u32_e32 v130, 32, v128
	v_ashrrev_i32_e32 v131, 31, v130
	v_lshlrev_b64 v[142:143], 8, v[130:131]
	v_lshl_add_u64 v[138:139], s[12:13], 0, v[142:143]
	v_lshl_add_u64 v[142:143], s[14:15], 0, v[142:143]
	v_lshl_add_u64 v[138:139], v[138:139], 0, v[136:137]
	v_lshl_add_u64 v[142:143], v[142:143], 0, v[136:137]
	v_mad_i64_i32 v[130:131], s[6:7], v130, s28, v[132:133]
	v_lshl_add_u64 v[130:131], v[130:131], 0, s[4:5]
	v_lshl_add_u64 v[130:131], v[130:131], 0, v[134:135]
	s_waitcnt vmcnt(14)
	v_mov_b32_e32 v138, v198
	v_mov_b32_e32 v139, v199
	v_mov_b32_e32 v140, v200
	v_mov_b32_e32 v141, v201
	v_mov_b32_e32 v142, v202
	v_mov_b32_e32 v143, v203
	v_mov_b32_e32 v144, v204
	v_mov_b32_e32 v145, v205
	v_pk_mul_f32 v[146:147], v[88:89], v[144:145] op_sel_hi:[1,0]
	s_nop 0
	v_pk_fma_f32 v[170:171], v[88:89], v[140:141], v[146:147] op_sel:[0,0,1] op_sel_hi:[1,1,0] neg_lo:[0,0,1] neg_hi:[0,0,1]
	v_pk_fma_f32 v[146:147], v[88:89], v[140:141], v[146:147] op_sel:[0,0,1] op_sel_hi:[1,0,0]
	v_mov_b32_e32 v156, v145
	v_mov_b32_e32 v146, v141
	v_pk_mul_f32 v[168:169], v[90:91], v[156:157] op_sel_hi:[1,0]
	v_pk_mul_f32 v[186:187], v[94:95], v[142:143] op_sel:[0,1]
	v_pk_fma_f32 v[172:173], v[90:91], v[146:147], v[168:169] op_sel:[0,0,1] op_sel_hi:[1,0,0] neg_lo:[0,0,1] neg_hi:[0,0,1]
	v_pk_fma_f32 v[174:175], v[90:91], v[146:147], v[168:169] op_sel:[0,0,1] op_sel_hi:[1,0,0]
	v_pk_mul_f32 v[168:169], v[92:93], v[142:143] op_sel_hi:[1,0]
	v_pk_fma_f32 v[188:189], v[94:95], v[138:139], v[186:187] op_sel:[0,1,1] op_sel_hi:[1,1,0] neg_lo:[0,0,1] neg_hi:[0,0,1]
	v_pk_fma_f32 v[176:177], v[92:93], v[138:139], v[168:169] op_sel:[0,0,1] op_sel_hi:[1,1,0] neg_lo:[0,0,1] neg_hi:[0,0,1]
	v_pk_fma_f32 v[168:169], v[92:93], v[138:139], v[168:169] op_sel:[0,0,1] op_sel_hi:[1,0,0]
	v_pk_fma_f32 v[186:187], v[94:95], v[138:139], v[186:187] op_sel:[0,1,1] op_sel_hi:[1,1,0]
	v_cvt_pk_bf16_f32 v168, v176, v169
	v_cvt_pk_bf16_f32 v169, v188, v187
	v_cvt_pk_bf16_f32 v170, v170, v147
	v_cvt_pk_bf16_f32 v171, v172, v175
	v_pk_mul_f32 v[144:145], v[80:81], v[144:145] op_sel_hi:[1,0]
	global_store_dwordx4 v[130:131], v[168:171], off
	s_nop 1
	v_pk_fma_f32 v[168:169], v[80:81], v[140:141], v[144:145] op_sel:[0,0,1] op_sel_hi:[1,1,0] neg_lo:[0,0,1] neg_hi:[0,0,1]
	v_pk_fma_f32 v[140:141], v[80:81], v[140:141], v[144:145] op_sel:[0,0,1] op_sel_hi:[1,0,0]
	v_pk_mul_f32 v[144:145], v[82:83], v[156:157] op_sel_hi:[1,0]
	v_cvt_pk_bf16_f32 v140, v168, v141
	v_pk_fma_f32 v[170:171], v[82:83], v[146:147], v[144:145] op_sel:[0,0,1] op_sel_hi:[1,0,0] neg_lo:[0,0,1] neg_hi:[0,0,1]
	v_pk_fma_f32 v[144:145], v[82:83], v[146:147], v[144:145] op_sel:[0,0,1] op_sel_hi:[1,0,0]
	v_pk_mul_f32 v[146:147], v[84:85], v[142:143] op_sel_hi:[1,0]
	v_pk_mul_f32 v[142:143], v[86:87], v[142:143] op_sel:[0,1]
	v_pk_fma_f32 v[172:173], v[84:85], v[138:139], v[146:147] op_sel:[0,0,1] op_sel_hi:[1,1,0] neg_lo:[0,0,1] neg_hi:[0,0,1]
	v_pk_fma_f32 v[146:147], v[84:85], v[138:139], v[146:147] op_sel:[0,0,1] op_sel_hi:[1,0,0]
	v_pk_fma_f32 v[174:175], v[86:87], v[138:139], v[142:143] op_sel:[0,1,1] op_sel_hi:[1,1,0] neg_lo:[0,0,1] neg_hi:[0,0,1]
	v_pk_fma_f32 v[138:139], v[86:87], v[138:139], v[142:143] op_sel:[0,1,1] op_sel_hi:[1,1,0]
	v_cvt_pk_bf16_f32 v141, v170, v145
	v_cvt_pk_bf16_f32 v138, v172, v147
	v_cvt_pk_bf16_f32 v139, v174, v139
	global_store_dwordx4 v[130:131], v[138:141], off offset:256
	v_add_u32_e32 v130, 48, v128
	v_ashrrev_i32_e32 v131, 31, v130
	v_lshlrev_b64 v[142:143], 8, v[130:131]
	v_lshl_add_u64 v[138:139], s[12:13], 0, v[142:143]
	v_lshl_add_u64 v[142:143], s[14:15], 0, v[142:143]
	v_lshl_add_u64 v[138:139], v[138:139], 0, v[136:137]
	v_lshl_add_u64 v[142:143], v[142:143], 0, v[136:137]
	v_mad_i64_i32 v[130:131], s[6:7], v130, s28, v[132:133]
	v_lshl_add_u64 v[130:131], v[130:131], 0, s[4:5]
	v_lshl_add_u64 v[130:131], v[130:131], 0, v[134:135]
	s_waitcnt vmcnt(14)
	v_mov_b32_e32 v138, v210
	v_mov_b32_e32 v139, v211
	v_mov_b32_e32 v140, v212
	v_mov_b32_e32 v141, v213
	v_mov_b32_e32 v142, v214
	v_mov_b32_e32 v143, v215
	v_mov_b32_e32 v144, v216
	v_mov_b32_e32 v145, v217
	v_pk_mul_f32 v[146:147], v[72:73], v[144:145] op_sel_hi:[1,0]
	s_nop 0
	v_pk_fma_f32 v[170:171], v[72:73], v[140:141], v[146:147] op_sel:[0,0,1] op_sel_hi:[1,1,0] neg_lo:[0,0,1] neg_hi:[0,0,1]
	v_pk_fma_f32 v[146:147], v[72:73], v[140:141], v[146:147] op_sel:[0,0,1] op_sel_hi:[1,0,0]
	v_mov_b32_e32 v156, v145
	v_mov_b32_e32 v146, v141
	v_pk_mul_f32 v[168:169], v[74:75], v[156:157] op_sel_hi:[1,0]
	v_pk_mul_f32 v[186:187], v[78:79], v[142:143] op_sel:[0,1]
	v_pk_fma_f32 v[172:173], v[74:75], v[146:147], v[168:169] op_sel:[0,0,1] op_sel_hi:[1,0,0] neg_lo:[0,0,1] neg_hi:[0,0,1]
	v_pk_fma_f32 v[174:175], v[74:75], v[146:147], v[168:169] op_sel:[0,0,1] op_sel_hi:[1,0,0]
	v_pk_mul_f32 v[168:169], v[76:77], v[142:143] op_sel_hi:[1,0]
	v_pk_fma_f32 v[188:189], v[78:79], v[138:139], v[186:187] op_sel:[0,1,1] op_sel_hi:[1,1,0] neg_lo:[0,0,1] neg_hi:[0,0,1]
	v_pk_fma_f32 v[176:177], v[76:77], v[138:139], v[168:169] op_sel:[0,0,1] op_sel_hi:[1,1,0] neg_lo:[0,0,1] neg_hi:[0,0,1]
	v_pk_fma_f32 v[168:169], v[76:77], v[138:139], v[168:169] op_sel:[0,0,1] op_sel_hi:[1,0,0]
	v_pk_fma_f32 v[186:187], v[78:79], v[138:139], v[186:187] op_sel:[0,1,1] op_sel_hi:[1,1,0]
	v_cvt_pk_bf16_f32 v168, v176, v169
	v_cvt_pk_bf16_f32 v169, v188, v187
	v_cvt_pk_bf16_f32 v170, v170, v147
	v_cvt_pk_bf16_f32 v171, v172, v175
	v_pk_mul_f32 v[144:145], v[64:65], v[144:145] op_sel_hi:[1,0]
	global_store_dwordx4 v[130:131], v[168:171], off
	s_nop 1
	v_pk_fma_f32 v[168:169], v[64:65], v[140:141], v[144:145] op_sel:[0,0,1] op_sel_hi:[1,1,0] neg_lo:[0,0,1] neg_hi:[0,0,1]
	v_pk_fma_f32 v[140:141], v[64:65], v[140:141], v[144:145] op_sel:[0,0,1] op_sel_hi:[1,0,0]
	v_pk_mul_f32 v[144:145], v[66:67], v[156:157] op_sel_hi:[1,0]
	v_cvt_pk_bf16_f32 v140, v168, v141
	v_pk_fma_f32 v[170:171], v[66:67], v[146:147], v[144:145] op_sel:[0,0,1] op_sel_hi:[1,0,0] neg_lo:[0,0,1] neg_hi:[0,0,1]
	v_pk_fma_f32 v[144:145], v[66:67], v[146:147], v[144:145] op_sel:[0,0,1] op_sel_hi:[1,0,0]
	v_pk_mul_f32 v[146:147], v[68:69], v[142:143] op_sel_hi:[1,0]
	v_pk_mul_f32 v[142:143], v[70:71], v[142:143] op_sel:[0,1]
	v_pk_fma_f32 v[172:173], v[68:69], v[138:139], v[146:147] op_sel:[0,0,1] op_sel_hi:[1,1,0] neg_lo:[0,0,1] neg_hi:[0,0,1]
	v_pk_fma_f32 v[146:147], v[68:69], v[138:139], v[146:147] op_sel:[0,0,1] op_sel_hi:[1,0,0]
	v_pk_fma_f32 v[174:175], v[70:71], v[138:139], v[142:143] op_sel:[0,1,1] op_sel_hi:[1,1,0] neg_lo:[0,0,1] neg_hi:[0,0,1]
	v_pk_fma_f32 v[138:139], v[70:71], v[138:139], v[142:143] op_sel:[0,1,1] op_sel_hi:[1,1,0]
	v_cvt_pk_bf16_f32 v141, v170, v145
	v_cvt_pk_bf16_f32 v138, v172, v147
	v_cvt_pk_bf16_f32 v139, v174, v139
	global_store_dwordx4 v[130:131], v[138:141], off offset:256
	v_add_u32_e32 v130, 0x80, v128
	v_ashrrev_i32_e32 v131, 31, v130
	v_lshlrev_b64 v[142:143], 8, v[130:131]
	v_lshl_add_u64 v[138:139], s[12:13], 0, v[142:143]
	v_lshl_add_u64 v[142:143], s[14:15], 0, v[142:143]
	v_lshl_add_u64 v[138:139], v[138:139], 0, v[136:137]
	v_lshl_add_u64 v[142:143], v[142:143], 0, v[136:137]
	v_mad_i64_i32 v[130:131], s[6:7], v130, s28, v[132:133]
	v_lshl_add_u64 v[130:131], v[130:131], 0, s[4:5]
	v_lshl_add_u64 v[130:131], v[130:131], 0, v[134:135]
	s_waitcnt vmcnt(14)
	v_mov_b32_e32 v138, v218
	v_mov_b32_e32 v139, v219
	v_mov_b32_e32 v140, v220
	v_mov_b32_e32 v141, v221
	v_mov_b32_e32 v142, v222
	v_mov_b32_e32 v143, v223
	v_mov_b32_e32 v144, v224
	v_mov_b32_e32 v145, v225
	v_pk_mul_f32 v[146:147], v[56:57], v[144:145] op_sel_hi:[1,0]
	s_nop 0
	v_pk_fma_f32 v[170:171], v[56:57], v[140:141], v[146:147] op_sel:[0,0,1] op_sel_hi:[1,1,0] neg_lo:[0,0,1] neg_hi:[0,0,1]
	v_pk_fma_f32 v[146:147], v[56:57], v[140:141], v[146:147] op_sel:[0,0,1] op_sel_hi:[1,0,0]
	v_mov_b32_e32 v156, v145
	v_mov_b32_e32 v146, v141
	v_pk_mul_f32 v[168:169], v[58:59], v[156:157] op_sel_hi:[1,0]
	v_pk_mul_f32 v[186:187], v[62:63], v[142:143] op_sel:[0,1]
	v_pk_fma_f32 v[172:173], v[58:59], v[146:147], v[168:169] op_sel:[0,0,1] op_sel_hi:[1,0,0] neg_lo:[0,0,1] neg_hi:[0,0,1]
	v_pk_fma_f32 v[174:175], v[58:59], v[146:147], v[168:169] op_sel:[0,0,1] op_sel_hi:[1,0,0]
	v_pk_mul_f32 v[168:169], v[60:61], v[142:143] op_sel_hi:[1,0]
	v_pk_fma_f32 v[188:189], v[62:63], v[138:139], v[186:187] op_sel:[0,1,1] op_sel_hi:[1,1,0] neg_lo:[0,0,1] neg_hi:[0,0,1]
	v_pk_fma_f32 v[176:177], v[60:61], v[138:139], v[168:169] op_sel:[0,0,1] op_sel_hi:[1,1,0] neg_lo:[0,0,1] neg_hi:[0,0,1]
	v_pk_fma_f32 v[168:169], v[60:61], v[138:139], v[168:169] op_sel:[0,0,1] op_sel_hi:[1,0,0]
	v_pk_fma_f32 v[186:187], v[62:63], v[138:139], v[186:187] op_sel:[0,1,1] op_sel_hi:[1,1,0]
	v_cvt_pk_bf16_f32 v168, v176, v169
	v_cvt_pk_bf16_f32 v169, v188, v187
	v_cvt_pk_bf16_f32 v170, v170, v147
	v_cvt_pk_bf16_f32 v171, v172, v175
	v_pk_mul_f32 v[144:145], v[48:49], v[144:145] op_sel_hi:[1,0]
	global_store_dwordx4 v[130:131], v[168:171], off
	s_nop 1
	v_pk_fma_f32 v[168:169], v[48:49], v[140:141], v[144:145] op_sel:[0,0,1] op_sel_hi:[1,1,0] neg_lo:[0,0,1] neg_hi:[0,0,1]
	v_pk_fma_f32 v[140:141], v[48:49], v[140:141], v[144:145] op_sel:[0,0,1] op_sel_hi:[1,0,0]
	v_pk_mul_f32 v[144:145], v[50:51], v[156:157] op_sel_hi:[1,0]
	v_cvt_pk_bf16_f32 v140, v168, v141
	v_pk_fma_f32 v[170:171], v[50:51], v[146:147], v[144:145] op_sel:[0,0,1] op_sel_hi:[1,0,0] neg_lo:[0,0,1] neg_hi:[0,0,1]
	v_pk_fma_f32 v[144:145], v[50:51], v[146:147], v[144:145] op_sel:[0,0,1] op_sel_hi:[1,0,0]
	v_pk_mul_f32 v[146:147], v[52:53], v[142:143] op_sel_hi:[1,0]
	v_pk_mul_f32 v[142:143], v[54:55], v[142:143] op_sel:[0,1]
	v_pk_fma_f32 v[172:173], v[52:53], v[138:139], v[146:147] op_sel:[0,0,1] op_sel_hi:[1,1,0] neg_lo:[0,0,1] neg_hi:[0,0,1]
	v_pk_fma_f32 v[146:147], v[52:53], v[138:139], v[146:147] op_sel:[0,0,1] op_sel_hi:[1,0,0]
	v_pk_fma_f32 v[174:175], v[54:55], v[138:139], v[142:143] op_sel:[0,1,1] op_sel_hi:[1,1,0] neg_lo:[0,0,1] neg_hi:[0,0,1]
	v_pk_fma_f32 v[138:139], v[54:55], v[138:139], v[142:143] op_sel:[0,1,1] op_sel_hi:[1,1,0]
	v_cvt_pk_bf16_f32 v141, v170, v145
	v_cvt_pk_bf16_f32 v138, v172, v147
	v_cvt_pk_bf16_f32 v139, v174, v139
	global_store_dwordx4 v[130:131], v[138:141], off offset:256
	v_add_u32_e32 v130, 0x90, v128
	v_ashrrev_i32_e32 v131, 31, v130
	v_lshlrev_b64 v[142:143], 8, v[130:131]
	v_lshl_add_u64 v[138:139], s[12:13], 0, v[142:143]
	v_lshl_add_u64 v[142:143], s[14:15], 0, v[142:143]
	v_lshl_add_u64 v[138:139], v[138:139], 0, v[136:137]
	v_lshl_add_u64 v[142:143], v[142:143], 0, v[136:137]
	v_mad_i64_i32 v[130:131], s[6:7], v130, s28, v[132:133]
	v_lshl_add_u64 v[130:131], v[130:131], 0, s[4:5]
	v_lshl_add_u64 v[130:131], v[130:131], 0, v[134:135]
	s_waitcnt vmcnt(14)
	v_mov_b32_e32 v138, v226
	v_mov_b32_e32 v139, v227
	v_mov_b32_e32 v140, v228
	v_mov_b32_e32 v141, v229
	v_mov_b32_e32 v142, v230
	v_mov_b32_e32 v143, v231
	v_mov_b32_e32 v144, v232
	v_mov_b32_e32 v145, v233
	v_pk_mul_f32 v[146:147], v[40:41], v[144:145] op_sel_hi:[1,0]
	s_nop 0
	v_pk_fma_f32 v[170:171], v[40:41], v[140:141], v[146:147] op_sel:[0,0,1] op_sel_hi:[1,1,0] neg_lo:[0,0,1] neg_hi:[0,0,1]
	v_pk_fma_f32 v[146:147], v[40:41], v[140:141], v[146:147] op_sel:[0,0,1] op_sel_hi:[1,0,0]
	v_mov_b32_e32 v156, v145
	v_mov_b32_e32 v146, v141
	v_pk_mul_f32 v[168:169], v[42:43], v[156:157] op_sel_hi:[1,0]
	v_pk_mul_f32 v[186:187], v[46:47], v[142:143] op_sel:[0,1]
	v_pk_fma_f32 v[172:173], v[42:43], v[146:147], v[168:169] op_sel:[0,0,1] op_sel_hi:[1,0,0] neg_lo:[0,0,1] neg_hi:[0,0,1]
	v_pk_fma_f32 v[174:175], v[42:43], v[146:147], v[168:169] op_sel:[0,0,1] op_sel_hi:[1,0,0]
	v_pk_mul_f32 v[168:169], v[44:45], v[142:143] op_sel_hi:[1,0]
	v_pk_fma_f32 v[188:189], v[46:47], v[138:139], v[186:187] op_sel:[0,1,1] op_sel_hi:[1,1,0] neg_lo:[0,0,1] neg_hi:[0,0,1]
	v_pk_fma_f32 v[176:177], v[44:45], v[138:139], v[168:169] op_sel:[0,0,1] op_sel_hi:[1,1,0] neg_lo:[0,0,1] neg_hi:[0,0,1]
	v_pk_fma_f32 v[168:169], v[44:45], v[138:139], v[168:169] op_sel:[0,0,1] op_sel_hi:[1,0,0]
	v_pk_fma_f32 v[186:187], v[46:47], v[138:139], v[186:187] op_sel:[0,1,1] op_sel_hi:[1,1,0]
	v_cvt_pk_bf16_f32 v168, v176, v169
	v_cvt_pk_bf16_f32 v169, v188, v187
	v_cvt_pk_bf16_f32 v170, v170, v147
	v_cvt_pk_bf16_f32 v171, v172, v175
	v_pk_mul_f32 v[144:145], v[32:33], v[144:145] op_sel_hi:[1,0]
	global_store_dwordx4 v[130:131], v[168:171], off
	s_nop 1
	v_pk_fma_f32 v[168:169], v[32:33], v[140:141], v[144:145] op_sel:[0,0,1] op_sel_hi:[1,1,0] neg_lo:[0,0,1] neg_hi:[0,0,1]
	v_pk_fma_f32 v[140:141], v[32:33], v[140:141], v[144:145] op_sel:[0,0,1] op_sel_hi:[1,0,0]
	v_pk_mul_f32 v[144:145], v[34:35], v[156:157] op_sel_hi:[1,0]
	v_cvt_pk_bf16_f32 v140, v168, v141
	v_pk_fma_f32 v[170:171], v[34:35], v[146:147], v[144:145] op_sel:[0,0,1] op_sel_hi:[1,0,0] neg_lo:[0,0,1] neg_hi:[0,0,1]
	v_pk_fma_f32 v[144:145], v[34:35], v[146:147], v[144:145] op_sel:[0,0,1] op_sel_hi:[1,0,0]
	v_pk_mul_f32 v[146:147], v[36:37], v[142:143] op_sel_hi:[1,0]
	v_pk_mul_f32 v[142:143], v[38:39], v[142:143] op_sel:[0,1]
	v_pk_fma_f32 v[172:173], v[36:37], v[138:139], v[146:147] op_sel:[0,0,1] op_sel_hi:[1,1,0] neg_lo:[0,0,1] neg_hi:[0,0,1]
	v_pk_fma_f32 v[146:147], v[36:37], v[138:139], v[146:147] op_sel:[0,0,1] op_sel_hi:[1,0,0]
	v_pk_fma_f32 v[174:175], v[38:39], v[138:139], v[142:143] op_sel:[0,1,1] op_sel_hi:[1,1,0] neg_lo:[0,0,1] neg_hi:[0,0,1]
	v_pk_fma_f32 v[138:139], v[38:39], v[138:139], v[142:143] op_sel:[0,1,1] op_sel_hi:[1,1,0]
	v_cvt_pk_bf16_f32 v141, v170, v145
	v_cvt_pk_bf16_f32 v138, v172, v147
	v_cvt_pk_bf16_f32 v139, v174, v139
	global_store_dwordx4 v[130:131], v[138:141], off offset:256
	v_add_u32_e32 v130, 0xa0, v128
	v_ashrrev_i32_e32 v131, 31, v130
	v_lshlrev_b64 v[142:143], 8, v[130:131]
	v_lshl_add_u64 v[138:139], s[12:13], 0, v[142:143]
	v_lshl_add_u64 v[142:143], s[14:15], 0, v[142:143]
	v_lshl_add_u64 v[138:139], v[138:139], 0, v[136:137]
	v_lshl_add_u64 v[142:143], v[142:143], 0, v[136:137]
	v_mad_i64_i32 v[130:131], s[6:7], v130, s28, v[132:133]
	v_lshl_add_u64 v[130:131], v[130:131], 0, s[4:5]
	v_lshl_add_u64 v[130:131], v[130:131], 0, v[134:135]
	s_waitcnt vmcnt(14)
	v_mov_b32_e32 v138, v234
	v_mov_b32_e32 v139, v235
	v_mov_b32_e32 v140, v236
	v_mov_b32_e32 v141, v237
	v_mov_b32_e32 v142, v238
	v_mov_b32_e32 v143, v239
	v_mov_b32_e32 v144, v240
	v_mov_b32_e32 v145, v241
	v_pk_mul_f32 v[146:147], v[24:25], v[144:145] op_sel_hi:[1,0]
	s_nop 0
	v_pk_fma_f32 v[170:171], v[24:25], v[140:141], v[146:147] op_sel:[0,0,1] op_sel_hi:[1,1,0] neg_lo:[0,0,1] neg_hi:[0,0,1]
	v_pk_fma_f32 v[146:147], v[24:25], v[140:141], v[146:147] op_sel:[0,0,1] op_sel_hi:[1,0,0]
	v_mov_b32_e32 v156, v145
	v_mov_b32_e32 v146, v141
	v_pk_mul_f32 v[168:169], v[26:27], v[156:157] op_sel_hi:[1,0]
	v_pk_mul_f32 v[186:187], v[30:31], v[142:143] op_sel:[0,1]
	v_pk_fma_f32 v[172:173], v[26:27], v[146:147], v[168:169] op_sel:[0,0,1] op_sel_hi:[1,0,0] neg_lo:[0,0,1] neg_hi:[0,0,1]
	v_pk_fma_f32 v[174:175], v[26:27], v[146:147], v[168:169] op_sel:[0,0,1] op_sel_hi:[1,0,0]
	v_pk_mul_f32 v[168:169], v[28:29], v[142:143] op_sel_hi:[1,0]
	v_pk_fma_f32 v[188:189], v[30:31], v[138:139], v[186:187] op_sel:[0,1,1] op_sel_hi:[1,1,0] neg_lo:[0,0,1] neg_hi:[0,0,1]
	v_pk_fma_f32 v[176:177], v[28:29], v[138:139], v[168:169] op_sel:[0,0,1] op_sel_hi:[1,1,0] neg_lo:[0,0,1] neg_hi:[0,0,1]
	v_pk_fma_f32 v[168:169], v[28:29], v[138:139], v[168:169] op_sel:[0,0,1] op_sel_hi:[1,0,0]
	v_pk_fma_f32 v[186:187], v[30:31], v[138:139], v[186:187] op_sel:[0,1,1] op_sel_hi:[1,1,0]
	v_cvt_pk_bf16_f32 v168, v176, v169
	v_cvt_pk_bf16_f32 v169, v188, v187
	v_cvt_pk_bf16_f32 v170, v170, v147
	v_cvt_pk_bf16_f32 v171, v172, v175
	v_pk_mul_f32 v[144:145], v[16:17], v[144:145] op_sel_hi:[1,0]
	global_store_dwordx4 v[130:131], v[168:171], off
	s_nop 1
	v_pk_fma_f32 v[168:169], v[16:17], v[140:141], v[144:145] op_sel:[0,0,1] op_sel_hi:[1,1,0] neg_lo:[0,0,1] neg_hi:[0,0,1]
	v_pk_fma_f32 v[140:141], v[16:17], v[140:141], v[144:145] op_sel:[0,0,1] op_sel_hi:[1,0,0]
	v_pk_mul_f32 v[144:145], v[18:19], v[156:157] op_sel_hi:[1,0]
	v_cvt_pk_bf16_f32 v140, v168, v141
	v_pk_fma_f32 v[170:171], v[18:19], v[146:147], v[144:145] op_sel:[0,0,1] op_sel_hi:[1,0,0] neg_lo:[0,0,1] neg_hi:[0,0,1]
	v_pk_fma_f32 v[144:145], v[18:19], v[146:147], v[144:145] op_sel:[0,0,1] op_sel_hi:[1,0,0]
	v_pk_mul_f32 v[146:147], v[20:21], v[142:143] op_sel_hi:[1,0]
	v_pk_mul_f32 v[142:143], v[22:23], v[142:143] op_sel:[0,1]
	v_pk_fma_f32 v[172:173], v[20:21], v[138:139], v[146:147] op_sel:[0,0,1] op_sel_hi:[1,1,0] neg_lo:[0,0,1] neg_hi:[0,0,1]
	v_pk_fma_f32 v[146:147], v[20:21], v[138:139], v[146:147] op_sel:[0,0,1] op_sel_hi:[1,0,0]
	v_pk_fma_f32 v[174:175], v[22:23], v[138:139], v[142:143] op_sel:[0,1,1] op_sel_hi:[1,1,0] neg_lo:[0,0,1] neg_hi:[0,0,1]
	v_pk_fma_f32 v[138:139], v[22:23], v[138:139], v[142:143] op_sel:[0,1,1] op_sel_hi:[1,1,0]
	v_add_u32_e32 v144, 0xb0, v128
	v_cvt_pk_bf16_f32 v138, v172, v147
	v_cvt_pk_bf16_f32 v139, v174, v139
	v_cvt_pk_bf16_f32 v141, v170, v145
	v_ashrrev_i32_e32 v145, 31, v144
	global_store_dwordx4 v[130:131], v[138:141], off offset:256
	v_mad_i64_i32 v[132:133], s[6:7], v144, s28, v[132:133]
	s_nop 0
	v_lshlrev_b64 v[138:139], 8, v[144:145]
	v_lshl_add_u64 v[128:129], s[12:13], 0, v[138:139]
	v_lshl_add_u64 v[138:139], s[14:15], 0, v[138:139]
	v_lshl_add_u64 v[128:129], v[128:129], 0, v[136:137]
	v_lshl_add_u64 v[136:137], v[138:139], 0, v[136:137]
	v_lshl_add_u64 v[132:133], v[132:133], 0, s[4:5]
	v_lshl_add_u64 v[132:133], v[132:133], 0, v[134:135]
	s_waitcnt vmcnt(14)
	v_mov_b32_e32 v128, v242
	v_mov_b32_e32 v129, v243
	v_mov_b32_e32 v130, v244
	v_mov_b32_e32 v131, v245
	v_mov_b32_e32 v136, v246
	v_mov_b32_e32 v137, v247
	v_mov_b32_e32 v138, v248
	v_mov_b32_e32 v139, v249
	v_pk_mul_f32 v[140:141], v[8:9], v[138:139] op_sel_hi:[1,0]
	s_nop 0
	v_pk_fma_f32 v[146:147], v[8:9], v[130:131], v[140:141] op_sel:[0,0,1] op_sel_hi:[1,0,0]
	v_mov_b32_e32 v156, v139
	v_pk_fma_f32 v[142:143], v[8:9], v[130:131], v[140:141] op_sel:[0,0,1] op_sel_hi:[1,1,0] neg_lo:[0,0,1] neg_hi:[0,0,1]
	v_mov_b32_e32 v146, v131
	v_pk_mul_f32 v[140:141], v[10:11], v[156:157] op_sel_hi:[1,0]
	v_pk_mul_f32 v[174:175], v[14:15], v[136:137] op_sel:[0,1]
	v_pk_fma_f32 v[168:169], v[10:11], v[146:147], v[140:141] op_sel:[0,0,1] op_sel_hi:[1,0,0] neg_lo:[0,0,1] neg_hi:[0,0,1]
	v_pk_fma_f32 v[170:171], v[10:11], v[146:147], v[140:141] op_sel:[0,0,1] op_sel_hi:[1,0,0]
	v_pk_mul_f32 v[140:141], v[12:13], v[136:137] op_sel_hi:[1,0]
	v_pk_fma_f32 v[176:177], v[14:15], v[128:129], v[174:175] op_sel:[0,1,1] op_sel_hi:[1,1,0] neg_lo:[0,0,1] neg_hi:[0,0,1]
	v_pk_fma_f32 v[172:173], v[12:13], v[128:129], v[140:141] op_sel:[0,0,1] op_sel_hi:[1,1,0] neg_lo:[0,0,1] neg_hi:[0,0,1]
	v_pk_fma_f32 v[140:141], v[12:13], v[128:129], v[140:141] op_sel:[0,0,1] op_sel_hi:[1,0,0]
	v_pk_fma_f32 v[174:175], v[14:15], v[128:129], v[174:175] op_sel:[0,1,1] op_sel_hi:[1,1,0]
	v_cvt_pk_bf16_f32 v140, v172, v141
	v_cvt_pk_bf16_f32 v141, v176, v175
	v_cvt_pk_bf16_f32 v142, v142, v147
	v_cvt_pk_bf16_f32 v143, v168, v171
	v_pk_mul_f32 v[134:135], v[0:1], v[138:139] op_sel_hi:[1,0]
	global_store_dwordx4 v[132:133], v[140:143], off
	v_pk_fma_f32 v[138:139], v[0:1], v[130:131], v[134:135] op_sel:[0,0,1] op_sel_hi:[1,1,0] neg_lo:[0,0,1] neg_hi:[0,0,1]
	v_pk_fma_f32 v[130:131], v[0:1], v[130:131], v[134:135] op_sel:[0,0,1] op_sel_hi:[1,0,0]
	v_pk_mul_f32 v[134:135], v[2:3], v[156:157] op_sel_hi:[1,0]
	v_pk_mul_f32 v[142:143], v[4:5], v[136:137] op_sel_hi:[1,0]
	v_pk_mul_f32 v[136:137], v[6:7], v[136:137] op_sel:[0,1]
	v_pk_fma_f32 v[140:141], v[2:3], v[146:147], v[134:135] op_sel:[0,0,1] op_sel_hi:[1,0,0] neg_lo:[0,0,1] neg_hi:[0,0,1]
	v_pk_fma_f32 v[134:135], v[2:3], v[146:147], v[134:135] op_sel:[0,0,1] op_sel_hi:[1,0,0]
	v_pk_fma_f32 v[144:145], v[4:5], v[128:129], v[142:143] op_sel:[0,0,1] op_sel_hi:[1,1,0] neg_lo:[0,0,1] neg_hi:[0,0,1]
	v_pk_fma_f32 v[142:143], v[4:5], v[128:129], v[142:143] op_sel:[0,0,1] op_sel_hi:[1,0,0]
	v_pk_fma_f32 v[146:147], v[6:7], v[128:129], v[136:137] op_sel:[0,1,1] op_sel_hi:[1,1,0] neg_lo:[0,0,1] neg_hi:[0,0,1]
	v_pk_fma_f32 v[128:129], v[6:7], v[128:129], v[136:137] op_sel:[0,1,1] op_sel_hi:[1,1,0]
	v_cvt_pk_bf16_f32 v130, v138, v131
	v_cvt_pk_bf16_f32 v128, v144, v143
	v_cvt_pk_bf16_f32 v129, v146, v129
	v_cvt_pk_bf16_f32 v131, v140, v135
	global_store_dwordx4 v[132:133], v[128:131], off offset:256
